# conversion quotas rebalanced (prologue 4450, G1 4000, G3 8200) on top of v24
# speedup vs baseline: 1.0027x; 1.0027x over previous
; #define PHASE_IDS() int tid = threadIdx.x; asm volatile("" : "+v"(tid)); const int lane = tid & 63, wid = __builtin_amdgcn_readfirstlane(tid >> 6), gw = bx * NWAVES + wid; (void)lane; (void)gw
; __device__ __forceinline__ void convert_items(const Args& A, unsigned char* ws, int g0, int g1, int w, int nw, float* scr, int lane) {
;     for (int it = g0 + w; it < g1; it += nw) {
;         const int l = it / PER_LAYER; int r = it % PER_LAYER;
;         if (r < I_IN) { const int nb = INW / 64, kb = r / nb, n0 = 64 * (r % nb); transpose_item(A.w_in + (size_t)l * DM * INW, DM, INW, (bf16*)(ws + WS_WIN + l * SZ_WIN), 64 * kb, n0, n0, A.norm1_g + l * DM + 64 * kb, scr, lane); continue; } r -= I_IN;
; __global__ void __launch_bounds__(NWAVES * 64, 2) fwd_kernel(Args A) {
;     ...
;     {
;         PHASE_IDS();
;         float* scr = (float*)(lds + wid * TSCR);
;         const bool lazy = (G == 256);
;         convert_items(A, ws, 0, lazy ? Q_P : N_ALL, gw, NGW, scr, lane);
.LBB0_6:
	s_or_b64 exec, exec, s[4:5]
	s_load_dwordx16 s[40:55], s[0:1], 0x0
	s_load_dwordx16 s[68:83], s[0:1], 0x40
	s_load_dword s14, s[0:1], 0x98
	s_add_i32 s0, 0, 0x23ff8
	v_mov_b32_e32 v1, s0
	s_lshl_b32 s0, s84, 3
	v_writelane_b32 v250, s0, 7
	v_mov_b32_e32 v2, v204
	s_waitcnt lgkmcnt(0)
	s_barrier
	ds_read_b32 v1, v1
	v_writelane_b32 v250, s1, 8
	s_mov_b32 s1, 0
	v_readfirstlane_b32 s0, v2
	s_ashr_i32 s18, s0, 6
	v_readlane_b32 s0, v250, 0
	s_lshl_b32 s0, s0, 3
	s_add_i32 s15, s18, s0
	s_cmpk_lg_i32 s84, 0x100
	v_writelane_b32 v250, s0, 9
	s_cselect_b64 s[4:5], -1, 0
	v_writelane_b32 v250, s4, 10
	s_cmpk_eq_i32 s84, 0x100
	s_cselect_b64 s[30:31], -1, 0
	v_writelane_b32 v250, s5, 11
	v_writelane_b32 v250, s40, 12
	s_movk_i32 s0, 0x1162
	s_and_b64 s[4:5], s[30:31], exec
	v_writelane_b32 v250, s41, 13
	v_writelane_b32 v250, s42, 14
	v_writelane_b32 v250, s43, 15
	v_writelane_b32 v250, s44, 16
	v_writelane_b32 v250, s45, 17
	v_writelane_b32 v250, s46, 18
	v_writelane_b32 v250, s47, 19
	v_writelane_b32 v250, s48, 20
	v_writelane_b32 v250, s49, 21
	v_writelane_b32 v250, s50, 22
	v_writelane_b32 v250, s51, 23
	v_writelane_b32 v250, s52, 24
	v_writelane_b32 v250, s53, 25
	v_writelane_b32 v250, s54, 26
	v_writelane_b32 v250, s55, 27
	v_writelane_b32 v250, s86, 28
	s_cselect_b32 s19, s0, 0xb000
	s_waitcnt lgkmcnt(0)
	v_readfirstlane_b32 s33, v1
	v_writelane_b32 v250, s87, 29
	v_writelane_b32 v250, s68, 30
	s_cmp_ge_i32 s15, s19
	v_and_b32_e32 v1, 63, v2
	v_writelane_b32 v250, s69, 31
	v_writelane_b32 v250, s70, 32
	v_writelane_b32 v250, s71, 33
	v_writelane_b32 v250, s72, 34
	v_writelane_b32 v250, s73, 35
	v_writelane_b32 v250, s74, 36
	v_writelane_b32 v250, s75, 37
	v_writelane_b32 v250, s76, 38
	v_writelane_b32 v250, s77, 39
	v_writelane_b32 v250, s78, 40
	v_writelane_b32 v250, s79, 41
	v_writelane_b32 v250, s80, 42
	v_writelane_b32 v250, s81, 43
	v_writelane_b32 v250, s82, 44
	v_writelane_b32 v250, s83, 45
	s_cbranch_scc1 .LBB0_40
	s_mul_i32 s0, s18, 0x4100
	s_add_i32 s0, s0, 0
	s_add_u32 s20, s86, 0x10a00000
	s_addc_u32 s21, s87, 0
	s_add_u32 s22, s86, 0x5a00000
	s_addc_u32 s23, s87, 0
	s_add_u32 s24, s86, 0x3a00000
	v_lshlrev_b32_e32 v3, 2, v1
	s_addc_u32 s25, s87, 0
	v_lshrrev_b32_e32 v13, 4, v1
	v_and_b32_e32 v4, 60, v3
	s_add_u32 s26, s86, 0x200000
	v_lshlrev_b32_e32 v3, 2, v4
	v_mul_u32_u24_e32 v5, 0x104, v13
	v_and_b32_e32 v2, 7, v2
	v_lshrrev_b32_e32 v19, 3, v1
	s_addc_u32 s27, s87, 0
	v_add3_u32 v18, s0, v3, v5
	v_lshlrev_b32_e32 v12, 3, v2
	v_mul_u32_u24_e32 v2, 0x820, v2
	v_lshlrev_b32_e32 v3, 2, v19
	s_cmp_lg_u64 s[78:79], 0
	v_add3_u32 v20, s0, v2, v3
	s_cselect_b64 s[4:5], -1, 0
	s_cmp_lg_u64 s[44:45], 0
	v_readlane_b32 s8, v250, 7
	v_mov_b32_e32 v11, 0
	v_or_b32_e32 v21, 8, v19
	v_or_b32_e32 v22, 16, v19
	v_or_b32_e32 v23, 24, v19
	v_or_b32_e32 v24, 32, v19
	v_or_b32_e32 v25, 40, v19
	v_or_b32_e32 v26, 48, v19
	v_or_b32_e32 v27, 56, v19
	s_cselect_b64 s[6:7], -1, 0
	s_lshl_b32 s28, s15, 6
	s_lshl_b32 s29, s8, 6
	s_lshl_b32 s34, s15, 1
	s_lshl_b32 s35, s8, 1
	s_mov_b32 s75, 0x8000
	s_mov_b32 s76, 0x10000
	s_mov_b32 s77, 0x18000
	s_mov_b32 s78, 0x20000
	s_mov_b32 s79, 0x28000
	s_mov_b32 s80, 0x30000
	s_mov_b32 s81, 0x38000
	s_mov_b32 s82, 0x40000
	s_mov_b32 s83, 0x48000
	s_mov_b32 s87, 0x50000
	s_mov_b32 s88, 0x58000
	s_mov_b32 s89, 0x60000
	s_mov_b32 s90, 0x68000
	s_mov_b32 s91, 0x70000
	s_mov_b32 s52, 0x78000
	v_add_u32_e32 v28, 0x410, v18
	v_add_u32_e32 v29, 0x418, v18
	v_add_u32_e32 v30, 0x820, v18
	v_add_u32_e32 v31, 0x828, v18
	v_add_u32_e32 v32, 0xc30, v18
	v_add_u32_e32 v33, 0xc38, v18
	v_add_u32_e32 v34, 0x1040, v18
	v_add_u32_e32 v35, 0x1048, v18
	v_add_u32_e32 v36, 0x1450, v18
	v_add_u32_e32 v37, 0x1458, v18
	v_add_u32_e32 v38, 0x1860, v18
	v_add_u32_e32 v39, 0x1868, v18
	v_add_u32_e32 v40, 0x1c70, v18
	v_add_u32_e32 v41, 0x1c78, v18
	v_add_u32_e32 v42, 0x2080, v18
	v_add_u32_e32 v43, 0x2088, v18
	v_add_u32_e32 v44, 0x2490, v18
	v_add_u32_e32 v45, 0x2498, v18
	v_add_u32_e32 v46, 0x28a0, v18
	v_add_u32_e32 v47, 0x28a8, v18
	v_add_u32_e32 v48, 0x2cb0, v18
	v_add_u32_e32 v49, 0x2cb8, v18
	v_add_u32_e32 v50, 0x30c0, v18
	v_add_u32_e32 v51, 0x30c8, v18
	v_add_u32_e32 v52, 0x34d0, v18
	v_add_u32_e32 v53, 0x34d8, v18
	v_add_u32_e32 v54, 0x38e0, v18
	v_add_u32_e32 v55, 0x38e8, v18
	v_add_u32_e32 v56, 0x3cf0, v18
	v_add_u32_e32 v57, 0x3cf8, v18
	s_mov_b32 s53, 0x16000
	s_mov_b32 s54, 0x2c000
	s_mov_b32 s55, 0x42000
	s_mov_b32 s56, 0x6e000
	s_mov_b32 s57, 0x84000
	s_mov_b32 s58, 0x9a000
	s_mov_b32 s59, 0xb0000
	v_lshlrev_b32_e32 v10, 2, v4
	v_lshlrev_b32_e32 v14, 1, v12
	v_add_u32_e32 v58, 0x400, v20
	s_mov_b32 s60, 0xc6000
	s_mov_b32 s61, 0xdc000
	s_mov_b32 s62, 0xf2000
	s_mov_b32 s63, 0x108000
	s_mov_b32 s64, 0x11e000
	s_mov_b32 s65, 0x134000
	s_mov_b32 s66, 0x14a000
	s_mov_b32 s67, s15
	v_readlane_b32 s9, v250, 8
	s_branch .LBB0_11

; __device__ __forceinline__ unsigned xb_ld(unsigned* p)              { return __hip_atomic_load(p, __ATOMIC_RELAXED, __HIP_MEMORY_SCOPE_AGENT); }
; #define PHASE_IDS() int tid = threadIdx.x; asm volatile("" : "+v"(tid)); const int lane = tid & 63, wid = __builtin_amdgcn_readfirstlane(tid >> 6), gw = bx * NWAVES + wid; (void)lane; (void)gw
; __global__ void __launch_bounds__(NWAVES * 64, 2) fwd_kernel(Args A) {
;     ...
;     bool tp = (G == 256);
;     if (tp) { for (unsigned q = 0; q < 16; ++q) { const unsigned c = xb_ld(&barw[XB_XCNT(q)]); tp = tp && (c == (q < 8 ? 32u : 0u)); } }
;     tp = __builtin_amdgcn_readfirstlane((int)tp) != 0;
;     const int vc = tp ? (int)(my_r * 8u + my_x) : bx;
;     ...
; #pragma nounroll
;     for (int l = 0; l < DEPTH; ++l) {
;         { pg8::Gemm g{XB, (const bf16*)(ws + WS_WIN + l * SZ_WIN), SEQ, INW, DM};
;           pg8::EpiZ E{Z, INW, 8, SS + (size_t)(SS_Q1 + l) * SEQ};
;           if (G == 256) { pg8::OrderTok S{vc, INW / 256, 0}; pg8::gemm_phase<pg8::EpiZ, pg8::OrderTok, true, true>(ldsl, g, S, E); }
;           else { pg8::StaticOrder S; S.init(SEQ, INW, G, bx); pg8::gemm_phase<pg8::EpiZ, pg8::StaticOrder, true, true>(ldsl, g, S, E); } }
;         if (G == 256 && vc >= 192) {
;             PHASE_IDS(); const int g0 = Q_P + l * (Q_G1 + Q_G3), g1 = g0 + Q_G1;
;             convert_items(A, ws, g0 < N_ALL ? g0 : N_ALL, g1 < N_ALL ? g1 : N_ALL, (vc - 192) * NWAVES + wid, 64 * NWAVES, (float*)(lds + wid * TSCR), lane); }
.LBB0_111:
	s_add_u32 s64, s86, 0x16200000
	s_addc_u32 s65, s87, 0
	s_add_u32 s80, s86, 0x10000
	s_addc_u32 s2, s87, 0
	s_add_u32 s82, s86, 0x18200000
	s_addc_u32 s83, s87, 0
	s_add_u32 s18, s86, 0x1ba00000
	s_addc_u32 s19, s87, 0
	s_add_u32 s20, s86, 0x1da00000
	v_cndmask_b32_e64 v0, 0, 1, s[0:1]
	s_addc_u32 s21, s87, 0
	v_readfirstlane_b32 s0, v0
	s_lshl_b32 s1, s33, 3
	s_and_b32 s0, 1, s0
	s_add_i32 s4, s1, s17
	s_cmp_eq_u32 s0, 1
	v_writelane_b32 v250, s2, 46
	s_cselect_b64 s[0:1], -1, 0
	s_and_b64 s[2:3], s[0:1], exec
	v_readlane_b32 s28, v250, 0
	s_cselect_b32 s3, s4, s28
	s_xor_b64 s[0:1], s[0:1], -1
	v_writelane_b32 v250, s0, 47
	v_mov_b32_e32 v2, 0
	v_mov_b32_e32 v205, 0x358637bd
	v_writelane_b32 v250, s1, 48
	s_add_u32 s0, s86, 0x200000
	v_writelane_b32 v250, s0, 49
	s_addc_u32 s0, s87, 0
	s_cmpk_lt_i32 s28, 0x1c0
	v_writelane_b32 v250, s0, 50
	s_cselect_b64 s[0:1], -1, 0
	v_writelane_b32 v250, s0, 51
	s_bfe_u32 s4, s3, 0x20003
	s_ashr_i32 s22, s3, 5
	v_writelane_b32 v250, s1, 52
	s_ashr_i32 s0, s28, 31
	v_writelane_b32 v250, s0, 53
	s_lshr_b32 s0, s0, 29
	s_add_i32 s0, s28, s0
	s_ashr_i32 s5, s0, 3
	s_and_b32 s0, s0, -8
	s_sub_i32 s6, s28, s0
	s_ashr_i32 s0, s84, 31
	v_writelane_b32 v250, s0, 54
	s_lshl_b32 s0, s3, 2
	s_and_b32 s0, s0, 28
	s_or_b32 s7, s0, s4
	s_cmp_lt_i32 s22, 14
	s_cselect_b64 s[0:1], -1, 0
	s_ashr_i32 s23, s22, 31
	v_writelane_b32 v250, s0, 55
	s_lshl_b32 s10, s7, 20
	s_lshl_b64 s[24:25], s[22:23], 20
	v_writelane_b32 v250, s1, 56
	s_add_u32 s0, s64, s10
	s_addc_u32 s1, s65, 0
	s_add_u32 s8, s0, 0x80000
	s_addc_u32 s9, s1, 0
	s_lshl_b32 s2, s7, 8
	v_writelane_b32 v250, s8, 57
	s_cmpk_gt_i32 s3, 0xbf
	s_mul_i32 s7, s7, 0x2c0000
	v_writelane_b32 v250, s9, 58
	s_cselect_b64 s[8:9], -1, 0
	v_writelane_b32 v250, s2, 59
	s_and_b64 s[8:9], s[30:31], s[8:9]
	v_writelane_b32 v250, s8, 60
	s_lshl_b32 s11, s3, 3
	s_add_i32 s2, s11, 0xb62
	v_writelane_b32 v250, s9, 61
	v_writelane_b32 v250, s2, 62
	s_add_u32 s2, s86, 0x10a00000
	v_writelane_b32 v250, s2, 63
	s_addc_u32 s2, s87, 0
	v_writelane_b32 v249, s2, 0
	s_add_u32 s2, s86, 0x5a00000
	v_writelane_b32 v249, s2, 1
	s_addc_u32 s2, s87, 0
	v_writelane_b32 v249, s2, 2
	s_add_u32 s2, s86, 0x3a00000
	v_writelane_b32 v249, s2, 3
	s_addc_u32 s2, s87, 0
	s_cmp_lg_u64 s[78:79], 0
	v_writelane_b32 v249, s2, 4
	s_cselect_b64 s[8:9], -1, 0
	v_writelane_b32 v249, s8, 5
	s_cmp_lg_u64 s[44:45], 0
	v_mov_b32_e32 v206, 0x260
	v_writelane_b32 v249, s9, 6
	s_cselect_b64 s[8:9], -1, 0
	v_writelane_b32 v249, s8, 7
	v_mov_b32_e32 v207, 1
	v_mbcnt_hi_u32_b32 v208, -1, v40
	v_writelane_b32 v249, s9, 8
	s_add_u32 s8, s86, 0x200
	s_addc_u32 s9, s87, 0
	v_writelane_b32 v249, s8, 9
	v_mov_b64_e32 v[160:161], 0x1c0
	v_mov_b64_e32 v[162:163], 0x1bf
	v_writelane_b32 v249, s9, 10
	s_add_u32 s8, s86, 0x1000
	s_addc_u32 s9, s87, 0
	v_writelane_b32 v249, s8, 11
	v_mov_b32_e32 v209, 0x41b17218
	v_mov_b32_e32 v210, 0x1a00
	v_writelane_b32 v249, s9, 12
	s_add_u32 s8, s86, 0x1100
	s_addc_u32 s9, s87, 0
	v_writelane_b32 v249, s8, 13
	v_mov_b32_e32 v211, 0x1800
	v_mov_b64_e32 v[164:165], 0x100
	v_writelane_b32 v249, s9, 14
	s_add_u32 s8, s86, 0x1200
	s_addc_u32 s9, s87, 0
	v_writelane_b32 v249, s8, 15
	v_mov_b64_e32 v[166:167], 0xff
	v_mov_b64_e32 v[168:169], 0x580
	v_writelane_b32 v249, s9, 16
	s_add_u32 s8, s86, 0x1300
	s_addc_u32 s9, s87, 0
	v_writelane_b32 v249, s8, 17
	s_cmp_eq_u32 s17, 15
	v_mov_b64_e32 v[170:171], 0x57f
	v_writelane_b32 v249, s9, 18
	s_cselect_b64 s[8:9], -1, 0
	v_writelane_b32 v249, s8, 19
	s_cmp_eq_u32 s17, 14
	s_mov_b32 s97, 0xf800000
	v_writelane_b32 v249, s9, 20
	s_cselect_b64 s[8:9], -1, 0
	v_writelane_b32 v249, s8, 21
	s_cmp_eq_u32 s17, 13
	s_movk_i32 s33, 0x90
	v_writelane_b32 v249, s9, 22
	s_cselect_b64 s[8:9], -1, 0
	v_writelane_b32 v249, s8, 23
	s_cmp_eq_u32 s17, 12
	s_mov_b32 s72, 0x3e38aa3b
	v_writelane_b32 v249, s9, 24
	s_cselect_b64 s[8:9], -1, 0
	v_writelane_b32 v249, s8, 25
	s_cmp_eq_u32 s17, 11
	s_mov_b32 s54, 0
	v_writelane_b32 v249, s9, 26
	s_cselect_b64 s[8:9], -1, 0
	v_writelane_b32 v249, s8, 27
	s_cmp_eq_u32 s17, 10
	s_mov_b32 s77, 0
	v_writelane_b32 v249, s9, 28
	s_cselect_b64 s[8:9], -1, 0
	v_writelane_b32 v249, s8, 29
	s_cmp_eq_u32 s17, 9
	s_mov_b32 s90, 0x3e6d3388
	v_writelane_b32 v249, s9, 30
	s_cselect_b64 s[8:9], -1, 0
	v_writelane_b32 v249, s8, 31
	s_cmp_eq_u32 s17, 8
	s_mov_b32 s92, 0x3f07dc22
	v_writelane_b32 v249, s9, 32
	s_cselect_b64 s[8:9], -1, 0
	v_writelane_b32 v249, s8, 33
	s_cmp_eq_u32 s17, 7
	s_mov_b32 s94, 0x3f35f0e3
	v_writelane_b32 v249, s9, 34
	s_cselect_b64 s[8:9], -1, 0
	v_writelane_b32 v249, s8, 35
	s_cmp_eq_u32 s17, 6
	s_mov_b32 s96, 0xbe11a98e
	v_writelane_b32 v249, s9, 36
	s_cselect_b64 s[8:9], -1, 0
	v_writelane_b32 v249, s8, 37
	s_cmp_eq_u32 s17, 5
	s_nop 0
	v_writelane_b32 v249, s9, 38
	s_cselect_b64 s[8:9], -1, 0
	v_writelane_b32 v249, s8, 39
	s_cmp_eq_u32 s17, 4
	s_nop 0
	v_writelane_b32 v249, s9, 40
	s_cselect_b64 s[8:9], -1, 0
	v_writelane_b32 v249, s8, 41
	s_cmp_eq_u32 s17, 3
	s_nop 0
	v_writelane_b32 v249, s9, 42
	s_cselect_b64 s[8:9], -1, 0
	v_writelane_b32 v249, s8, 43
	s_cmp_eq_u32 s17, 2
	s_nop 0
	v_writelane_b32 v249, s9, 44
	s_cselect_b64 s[8:9], -1, 0
	v_writelane_b32 v249, s8, 45
	s_cmp_eq_u32 s17, 1
	s_nop 0
	v_writelane_b32 v249, s9, 46
	s_cselect_b64 s[8:9], -1, 0
	v_writelane_b32 v249, s8, 47
	s_cmp_eq_u32 s17, 0
	s_nop 0
	v_writelane_b32 v249, s9, 48
	s_cselect_b64 s[8:9], -1, 0
	v_writelane_b32 v249, s8, 49
	s_lshl_b32 s2, s17, 8
	s_nop 0
	v_writelane_b32 v249, s9, 50
	s_add_u32 s8, s86, s2
	s_addc_u32 s9, s87, 0
	s_add_u32 s12, s8, 0x1400
	s_addc_u32 s13, s9, 0
	v_writelane_b32 v249, s12, 51
	s_nop 1
; #define PHASE_IDS() int tid = threadIdx.x; asm volatile("" : "+v"(tid)); const int lane = tid & 63, wid = __builtin_amdgcn_readfirstlane(tid >> 6), gw = bx * NWAVES + wid; (void)lane; (void)gw
; __device__ __forceinline__ void mixer_phase256(const Args& A, int l, int vc, const bf16* Z, bf16* MIX, ss_t* ssa, ss_t* ssb, unsigned char* lds, int tid, int wid, int lane) {
;     ...
;     const int gx = vc & 7, gj = vc >> 3;
;     const int n = 8 * gx + (gj >> 2), kvh = gj & 3, h = gj & 15, cb = 8 * gx + 4 * (gj >> 4);
;     const int fr = lane & 15, fq = lane >> 4;
;     const bool isK = tid < 256; const int arow = tid & 255; const int atok = (n - 1) * 128 + arow;
;     u32x4 aw[8], sw[8];
;     { const bf16* ap = Z + (size_t)(atok < 0 ? 0 : atok) * INW + (isK ? KCOL : VCOL) + kvh * 64;
; #pragma unroll
;       for (int c = 0; c < 8; ++c) aw[c] = *(const u32x4*)(ap + 8 * c); }
;     const int srow = tid & 127, sj = tid >> 7;
;     { const bf16* sp = Z + (size_t)((cb + sj) * 128 + srow) * INW + 1024 + h * 64;
; #pragma unroll
;       for (int c = 0; c < 8; ++c) sw[c] = *(const u32x4*)(sp + 8 * c); }
;     const int st = 16 * wid + fr; const int nks = (wid >> 1) + 1;
;     const float* wrow = A.sgu_w + ((size_t)(l * 16 + h) * 128 + st) * 128;
; __global__ void __launch_bounds__(NWAVES * 64, 2) fwd_kernel(Args A) {
;     ...
;         if (G == 256 && vc >= 128) {
;             PHASE_IDS(); const int g0 = Q_P + l * (Q_G1 + Q_G3) + Q_G1, g1 = g0 + Q_G3;
;             convert_items(A, ws, g0 < N_ALL ? g0 : N_ALL, g1 < N_ALL ? g1 : N_ALL, (vc - 128) * NWAVES + wid, 128 * NWAVES, (float*)(lds + wid * TSCR), lane); }
	v_writelane_b32 v249, s13, 52
	s_add_u32 s12, s8, 0x2400
	s_addc_u32 s13, s9, 0
	v_writelane_b32 v249, s12, 53
	s_nop 1
	v_writelane_b32 v249, s13, 54
	s_add_u32 s12, s86, 0x3400
	s_addc_u32 s13, s87, 0
	v_writelane_b32 v249, s12, 55
	s_nop 1
	v_writelane_b32 v249, s13, 56
	s_add_u32 s12, s86, 0x3500
	s_addc_u32 s13, s87, 0
	v_writelane_b32 v249, s12, 57
	s_cmpk_lt_i32 s28, 0x100
	s_nop 0
	v_writelane_b32 v249, s13, 58
	s_cselect_b64 s[12:13], -1, 0
	v_writelane_b32 v249, s12, 59
	s_cmpk_lt_i32 s28, 0x400
	s_nop 0
	v_writelane_b32 v249, s13, 60
	s_cselect_b64 s[12:13], -1, 0
	v_writelane_b32 v249, s12, 61
	s_and_b32 s2, s11, 56
	s_nop 0
	v_writelane_b32 v249, s13, 62
	s_and_b32 s12, s22, -4
	s_add_i32 s14, s2, s12
	s_add_i32 s12, s2, s22
	s_ashr_i32 s2, s3, 3
	s_and_b32 s13, s2, 3
	s_and_b32 s17, s2, 15
	s_lshl_b32 s2, s13, 6
	s_lshl_b32 s23, s13, 2
	s_lshl_b32 s13, s13, 8
	v_writelane_b32 v248, s13, 0
	s_lshl_b32 s13, s12, 7
	v_writelane_b32 v248, s13, 1
	s_addk_i32 s13, 0xff80
	v_writelane_b32 v248, s13, 2
	s_lshl_b32 s13, s17, 7
	s_add_u32 s26, s82, s13
	v_writelane_b32 v248, s17, 3
	s_addc_u32 s27, s83, 0
	v_writelane_b32 v248, s26, 4
	v_writelane_b32 v249, s23, 63
	s_nop 0
	v_writelane_b32 v248, s27, 5
	v_writelane_b32 v248, s14, 6
	s_lshl_b32 s14, s14, 7
	s_or_b32 s17, s14, 0x80
	v_writelane_b32 v248, s17, 7
	s_or_b32 s17, s14, 0x100
	v_writelane_b32 v248, s17, 8
	v_writelane_b32 v248, s14, 9
	s_or_b32 s14, s14, 0x180
	s_add_u32 s26, s18, s13
	v_writelane_b32 v248, s14, 10
	s_addc_u32 s27, s19, 0
	v_writelane_b32 v248, s26, 11
	s_cmp_gt_i32 s12, 0
	s_cselect_b64 s[12:13], -1, 0
	v_writelane_b32 v248, s27, 12
	v_writelane_b32 v248, s12, 13
	s_nop 1
	v_writelane_b32 v248, s13, 14
	s_add_u32 s12, s8, 0x4000
	s_addc_u32 s13, s9, 0
	v_writelane_b32 v248, s12, 15
	s_add_u32 s8, s8, 0x5000
	s_addc_u32 s9, s9, 0
	v_writelane_b32 v248, s13, 16
	s_lshl_b32 s12, s6, 5
	v_writelane_b32 v248, s8, 17
	s_cmp_lt_i32 s22, 8
	s_nop 0
	v_writelane_b32 v248, s9, 18
	s_cselect_b64 s[8:9], -1, 0
	s_add_u32 s88, s18, s10
	v_writelane_b32 v248, s8, 19
	s_addc_u32 s89, s19, 0
	s_nop 0
	v_writelane_b32 v248, s9, 20
	s_add_u32 s8, s88, 0x80000
	s_addc_u32 s9, s89, 0
	v_writelane_b32 v248, s8, 21
	s_cmpk_lt_i32 s28, 0x580
	s_mov_b64 s[28:29], 0x80
	v_writelane_b32 v248, s9, 22
	s_cselect_b64 s[8:9], -1, 0
	v_writelane_b32 v248, s8, 23
	s_add_i32 s26, s22, 32
	s_cmp_lt_i32 s22, 12
	v_writelane_b32 v248, s9, 24
	s_mov_b32 s8, s22
	v_writelane_b32 v248, s8, 25
	s_nop 1
	v_writelane_b32 v248, s9, 26
	s_cselect_b64 s[8:9], -1, 0
	v_writelane_b32 v248, s8, 27
	s_ashr_i32 s27, s26, 31
	s_nop 0
	v_writelane_b32 v248, s9, 28
	s_mov_b32 s8, s26
	v_writelane_b32 v248, s8, 29
	s_nop 1
	v_writelane_b32 v248, s9, 30
	s_lshl_b64 s[8:9], s[26:27], 20
	v_writelane_b32 v248, s8, 31
	s_cmpk_gt_i32 s3, 0x7f
	s_nop 0
	v_writelane_b32 v248, s9, 32
	s_cselect_b64 s[8:9], -1, 0
	s_and_b64 s[8:9], s[30:31], s[8:9]
	v_writelane_b32 v248, s8, 33
	s_mov_b32 s30, 0x3e027906
	s_nop 0
	v_writelane_b32 v248, s9, 34
	s_add_i32 s8, s11, 0x1d02
	s_add_u32 s34, s20, s7
	s_addc_u32 s35, s21, 0
	v_writelane_b32 v248, s8, 35
	s_add_u32 s8, s34, 0x160000
	s_addc_u32 s9, s35, 0
	v_writelane_b32 v248, s8, 36
	s_cmp_lt_i32 s6, 0
	s_mul_i32 s7, s6, 33
	v_writelane_b32 v248, s9, 37
	s_cselect_b32 s8, 57, 56
	s_mul_i32 s8, s6, s8
	s_movk_i32 s9, 0xb1
	s_cselect_b32 s7, s7, s12
	s_cselect_b32 s9, s9, 0xb0
	s_add_i32 s8, s8, s5
	s_mul_hi_i32 s10, s8, 0x92492493
	s_add_i32 s10, s10, s8
	s_lshr_b32 s11, s10, 31
	s_ashr_i32 s10, s10, 6
	s_add_i32 s10, s10, s11
	s_mul_i32 s11, s10, 0x70
	s_sub_i32 s8, s8, s11
	s_bfe_i32 s11, s8, 0x80000
	s_bfe_u32 s11, s11, 0x3000c
	s_add_i32 s11, s8, s11
	s_and_b32 s12, s11, 0xf8
	s_add_i32 s7, s7, s5
	s_sub_i32 s8, s8, s12
	s_ashr_i32 s12, s7, 31
	s_mul_i32 s6, s6, s9
	s_lshr_b32 s12, s12, 26
	s_add_i32 s6, s6, s5
	s_add_i32 s12, s7, s12
	s_mul_hi_i32 s5, s6, 0x2e8ba2e9
	s_and_b32 s13, s12, 0xffc0
	s_lshr_b32 s9, s5, 31
	s_ashr_i32 s5, s5, 6
	s_sub_i32 s7, s7, s13
	s_add_i32 s5, s5, s9
	s_bfe_i32 s13, s7, 0x80000
	s_mul_i32 s9, s5, 0x160
	s_bfe_u32 s13, s13, 0x3000c
	s_sub_i32 s6, s6, s9
; #define GRID_BAR() xcd_barrier(bar)
; __global__ void __launch_bounds__(NWAVES * 64, 2) fwd_kernel(Args A) {
;     ...
;         { pg8::Gemm g{XB, (const bf16*)(ws + WS_WIN + l * SZ_WIN), SEQ, INW, DM};
;           pg8::EpiZ E{Z, INW, 8, SS + (size_t)(SS_Q1 + l) * SEQ};
;           if (G == 256) { pg8::OrderTok S{vc, INW / 256, 0}; pg8::gemm_phase<pg8::EpiZ, pg8::OrderTok, true, true>(ldsl, g, S, E); }
;           else { pg8::StaticOrder S; S.init(SEQ, INW, G, bx); pg8::gemm_phase<pg8::EpiZ, pg8::StaticOrder, true, true>(ldsl, g, S, E); } }
;         if (G == 256 && vc >= 192) {
;             PHASE_IDS(); const int g0 = Q_P + l * (Q_G1 + Q_G3), g1 = g0 + Q_G1;
;             convert_items(A, ws, g0 < N_ALL ? g0 : N_ALL, g1 < N_ALL ? g1 : N_ALL, (vc - 192) * NWAVES + wid, 64 * NWAVES, (float*)(lds + wid * TSCR), lane); }
;         GRID_BAR();
;         { PHASE_IDS();
;           if (G == 256) mixer_phase256(A, l, vc, Z, MIX, SS + (size_t)(SS_A + l) * SEQ, SS + (size_t)(SS_B + l) * SEQ, lds, tid, wid, lane);
;           else {
;             for (int a = bx; a < 256; a += G) attn_unit(A, l, a >> 2, a & 3, Z, MIX, SS + (size_t)(SS_B + l) * SEQ, lds, tid, wid, lane);
;             for (int s = bx; s < 1024; s += G) sgu_unit(A, l, s >> 4, s & 15, Z, MIX, SS + (size_t)(SS_A + l) * SEQ, lds, tid, wid, lane); } }
;         LOCAL_BAR();
;         { pg8::Gemm g{MIX, (const bf16*)(ws + WS_WOUT + l * SZ_WOUT), SEQ, DM, DM};
;           pg8::EpiResid<true> E{nullptr, DM, XB, SS + (size_t)(SS_Q2 + l) * SEQ, SS + (size_t)(SS_A + l) * SEQ, SS + (size_t)(SS_B + l) * SEQ};
;           if (G == 256) { pg8::OrderTok S{vc, DM / 256, 0}; pg8::gemm_phase<pg8::EpiResid<true>, pg8::OrderTok, true, true>(ldsl, g, S, E); }
;           else { pg8::StaticOrder S; S.init(SEQ, DM, G, bx); pg8::gemm_phase<pg8::EpiResid<true>, pg8::StaticOrder, true, true>(ldsl, g, S, E); } }
;         LOCAL_BAR();
;         { pg8::Gemm g{XB, (const bf16*)(ws + WS_WGU + l * SZ_WGU), SEQ, NGU, DM};
;           pg8::EpiSwiGLU E{ACT, DFF, SS + (size_t)(SS_Q2 + l) * SEQ};
;           if (G == 256) { pg8::OrderTok S{vc, NGU / 256, 5}; pg8::gemm_phase<pg8::EpiSwiGLU, pg8::OrderTok, true, true>(ldsl, g, S, E); }
;           else { pg8::StaticOrder S; S.init(SEQ, NGU, G, bx); pg8::gemm_phase<pg8::EpiSwiGLU, pg8::StaticOrder, true, true>(ldsl, g, S, E); } }
;         if (G == 256 && vc >= 128) {
	s_add_i32 s13, s7, s13
	s_bfe_u32 s9, s6, 0x3001c
	s_and_b32 s14, s13, 0xf8
	s_add_i32 s9, s6, s9
	s_lshl_b32 s10, s10, 3
	s_sext_i32_i8 s8, s8
	s_sub_i32 s7, s7, s14
	s_and_b32 s14, s9, 0xfff8
	s_add_i32 s22, s10, s8
	s_ashr_i32 s8, s12, 6
	s_sub_i32 s6, s6, s14
	s_lshl_b32 s8, s8, 3
	s_sext_i32_i8 s7, s7
	s_add_i32 s12, s8, s7
	s_lshl_b32 s5, s5, 3
	s_sext_i32_i16 s7, s9
	s_sext_i32_i16 s6, s6
	s_add_i32 s26, s5, s6
	s_lshr_b32 s6, s7, 3
	s_ashr_i32 s5, s7, 3
	s_bfe_i64 s[6:7], s[6:7], 0x100000
	s_bfe_i32 s11, s11, 0x80000
	v_writelane_b32 v248, s5, 38
	s_lshl_b64 s[6:7], s[6:7], 20
	s_sext_i32_i16 s11, s11
	s_bfe_i32 s10, s13, 0x80000
	v_writelane_b32 v248, s6, 39
	s_sext_i32_i16 s10, s10
	s_ashr_i32 s5, s11, 3
	v_writelane_b32 v248, s7, 40
	v_writelane_b32 v248, s5, 41
	s_ashr_i32 s5, s10, 3
	v_writelane_b32 v248, s5, 42
	s_lshr_b32 s8, s10, 3
	s_mov_b32 s10, s26
	s_ashr_i32 s27, s26, 31
	s_lshr_b32 s6, s11, 3
	v_writelane_b32 v248, s10, 43
	s_mul_i32 s5, s85, s84
	s_mul_i32 s5, s5, s16
	v_writelane_b32 v248, s11, 44
	s_lshl_b64 s[10:11], s[26:27], 20
	s_add_u32 s10, s64, s10
	s_addc_u32 s11, s65, s11
	s_add_u32 s26, s10, 0x80000
	v_writelane_b32 v248, s10, 45
	s_addc_u32 s27, s11, 0
	s_bfe_i64 s[6:7], s[6:7], 0x100000
	v_writelane_b32 v248, s11, 46
	v_writelane_b32 v248, s26, 47
	s_lshl_b64 s[6:7], s[6:7], 20
	s_ashr_i32 s23, s22, 31
	v_writelane_b32 v248, s27, 48
	v_writelane_b32 v248, s6, 49
	s_movk_i32 s85, 0x1c00
	s_nop 0
	v_writelane_b32 v248, s7, 50
	s_mov_b32 s6, s22
	v_writelane_b32 v248, s6, 51
	s_nop 1
	v_writelane_b32 v248, s7, 52
	s_lshl_b64 s[6:7], s[22:23], 20
	s_add_u32 s6, s64, s6
	s_addc_u32 s7, s65, s7
	s_add_u32 s10, s6, 0x80000
	v_writelane_b32 v248, s6, 53
	s_addc_u32 s11, s7, 0
	s_ashr_i32 s13, s12, 31
	v_writelane_b32 v248, s7, 54
	v_writelane_b32 v248, s10, 55
	s_bfe_i64 s[6:7], s[8:9], 0x100000
	s_lshl_b64 s[6:7], s[6:7], 20
	v_writelane_b32 v248, s11, 56
	v_writelane_b32 v248, s6, 57
	s_nop 1
	v_writelane_b32 v248, s7, 58
	s_lshl_b64 s[6:7], s[12:13], 20
	s_add_u32 s6, s18, s6
	v_writelane_b32 v248, s18, 59
	s_addc_u32 s7, s19, s7
	s_add_u32 s8, s6, 0x80000
	v_writelane_b32 v248, s19, 60
	v_writelane_b32 v248, s5, 61
	v_writelane_b32 v248, s6, 62
	s_addc_u32 s9, s7, 0
	v_writelane_b32 v247, s8, 0
	v_writelane_b32 v248, s7, 63
	s_mov_b32 s6, s12
	v_writelane_b32 v247, s9, 1
	v_writelane_b32 v247, s6, 2
	s_mul_hi_i32 s5, s12, 0x2c0000
	s_nop 0
	v_writelane_b32 v247, s7, 3
	s_mul_i32 s6, s12, 0x2c0000
	s_add_u32 s6, s20, s6
	v_writelane_b32 v247, s20, 4
	s_addc_u32 s7, s21, s5
	s_add_u32 s8, s6, 0x160000
	v_writelane_b32 v247, s21, 5
	v_writelane_b32 v247, s6, 6
	s_addc_u32 s9, s7, 0
	s_and_b32 s3, s3, 7
	v_writelane_b32 v247, s7, 7
	s_lshl_b32 s5, s3, 22
	s_lshl_b32 s6, s4, 20
	s_or_b32 s5, s5, s6
	s_add_u32 s31, s86, s5
	s_addc_u32 s91, s87, 0
	v_writelane_b32 v247, s8, 8
	s_add_u32 s6, s31, 0x16280080
	s_addc_u32 s7, s91, 0
	v_writelane_b32 v247, s9, 9
	v_writelane_b32 v247, s6, 10
	s_add_u32 s5, s86, s24
	s_mul_i32 s3, s3, 0xb00000
	v_writelane_b32 v247, s7, 11
	v_writelane_b32 v247, s24, 12
	s_addc_u32 s6, s87, s25
	s_add_u32 s8, s5, 0x200100
	v_writelane_b32 v247, s25, 13
	s_addc_u32 s9, s6, 0
	v_writelane_b32 v247, s8, 14
	s_mul_i32 s4, s4, 0x2c0000
	s_nop 0
	v_writelane_b32 v247, s9, 15
	s_add_u32 s8, s31, 0x1ba80080
	s_addc_u32 s9, s91, 0
	v_writelane_b32 v247, s8, 16
	s_nop 1
	v_writelane_b32 v247, s9, 17
	s_add_u32 s8, s5, 0x3a00100
	s_addc_u32 s9, s6, 0
	s_add_i32 s3, s3, s4
	s_add_u32 s93, s86, s3
	s_addc_u32 s95, s87, 0
	v_writelane_b32 v247, s8, 18
	s_add_u32 s4, s93, 0x1db60080
	s_addc_u32 s5, s95, 0
	v_writelane_b32 v247, s9, 19
	v_writelane_b32 v247, s4, 20
	s_add_i32 s3, 0, 0x23ff0
	s_lshl_b32 s2, s2, 1
	v_writelane_b32 v247, s5, 21
	v_writelane_b32 v247, s3, 22
	s_add_i32 s3, 0, 0x23ff4
	v_writelane_b32 v247, s3, 23
	s_add_i32 s3, 0, 0x11400
	v_writelane_b32 v247, s3, 24
	v_writelane_b32 v247, s2, 25
	s_nop 1
	v_writelane_b32 v247, s3, 26
	s_add_i32 s2, 0, 0x11c00
	v_writelane_b32 v247, s2, 27
	v_writelane_b32 v247, s64, 28
	s_nop 1
	v_writelane_b32 v247, s65, 29
	v_writelane_b32 v247, s80, 30
	s_branch .LBB0_116

; #define PHASE_IDS() int tid = threadIdx.x; asm volatile("" : "+v"(tid)); const int lane = tid & 63, wid = __builtin_amdgcn_readfirstlane(tid >> 6), gw = bx * NWAVES + wid; (void)lane; (void)gw
; __device__ __forceinline__ void convert_items(const Args& A, unsigned char* ws, int g0, int g1, int w, int nw, float* scr, int lane) {
;     for (int it = g0 + w; it < g1; it += nw) {
; __global__ void __launch_bounds__(NWAVES * 64, 2) fwd_kernel(Args A) {
;     ...
;         if (G == 256 && vc >= 192) {
;             PHASE_IDS(); const int g0 = Q_P + l * (Q_G1 + Q_G3), g1 = g0 + Q_G1;
;             convert_items(A, ws, g0 < N_ALL ? g0 : N_ALL, g1 < N_ALL ? g1 : N_ALL, (vc - 192) * NWAVES + wid, 64 * NWAVES, (float*)(lds + wid * TSCR), lane); }
.LBB0_213:
	v_readlane_b32 s2, v250, 60
	v_readlane_b32 s3, v250, 61
	v_readlane_b32 s40, v250, 12
	s_andn2_b64 vcc, exec, s[2:3]
	s_mul_i32 s81, s78, 0x2fa8
	v_readlane_b32 s42, v250, 14
	v_readlane_b32 s43, v250, 15
	v_readlane_b32 s44, v250, 16
	v_readlane_b32 s45, v250, 17
	v_readlane_b32 s46, v250, 18
	v_readlane_b32 s47, v250, 19
	v_readlane_b32 s48, v250, 20
	v_readlane_b32 s49, v250, 21
	v_readlane_b32 s50, v250, 22
	v_readlane_b32 s51, v250, 23
	v_readlane_b32 s52, v250, 24
	v_readlane_b32 s53, v250, 25
	v_readlane_b32 s54, v250, 26
	v_readlane_b32 s55, v250, 27
	v_readlane_b32 s41, v250, 13
	s_cbranch_vccnz .LBB0_249
	v_mov_b32_e32 v4, v204
	v_readlane_b32 s3, v250, 62
	v_readfirstlane_b32 s2, v4
	s_ashr_i32 s2, s2, 6
	s_add_i32 s3, s3, s81
	s_add_i32 s8, s81, 0x2102
	s_add_i32 s9, s3, s2
	s_cmp_ge_i32 s9, s8
	s_cbranch_scc1 .LBB0_249
	v_lshlrev_b32_e32 v0, 2, v4
	s_mulk_i32 s2, 0x4100
	v_bfe_u32 v1, v4, 4, 2
	v_and_b32_e32 v0, 60, v0
	s_add_i32 s2, s2, 0
	v_lshlrev_b32_e32 v3, 2, v0
	s_waitcnt lgkmcnt(0)
	v_mul_u32_u24_e32 v5, 0x104, v1
	v_add3_u32 v3, s2, v3, v5
	v_and_b32_e32 v5, 7, v4
	v_bfe_u32 v13, v4, 3, 3
	v_lshlrev_b32_e32 v12, 3, v5
	v_mul_u32_u24_e32 v4, 0x820, v5
	v_lshlrev_b32_e32 v5, 2, v13
	v_add3_u32 v16, s2, v4, v5
	v_or_b32_e32 v17, 8, v13
	v_or_b32_e32 v18, 16, v13
	v_or_b32_e32 v19, 24, v13
	v_or_b32_e32 v20, 32, v13
	v_or_b32_e32 v21, 40, v13
	v_or_b32_e32 v22, 48, v13
	v_or_b32_e32 v23, 56, v13
	s_lshl_b32 s10, s9, 6
	s_lshl_b32 s11, s9, 1
	s_branch .LBB0_219

; #define PHASE_IDS() int tid = threadIdx.x; asm volatile("" : "+v"(tid)); const int lane = tid & 63, wid = __builtin_amdgcn_readfirstlane(tid >> 6), gw = bx * NWAVES + wid; (void)lane; (void)gw
; __device__ __forceinline__ void convert_items(const Args& A, unsigned char* ws, int g0, int g1, int w, int nw, float* scr, int lane) {
;     for (int it = g0 + w; it < g1; it += nw) {
; __global__ void __launch_bounds__(NWAVES * 64, 2) fwd_kernel(Args A) {
;     ...
;         if (G == 256 && vc >= 128) {
;             PHASE_IDS(); const int g0 = Q_P + l * (Q_G1 + Q_G3) + Q_G1, g1 = g0 + Q_G3;
;             convert_items(A, ws, g0 < N_ALL ? g0 : N_ALL, g1 < N_ALL ? g1 : N_ALL, (vc - 128) * NWAVES + wid, 128 * NWAVES, (float*)(lds + wid * TSCR), lane); }
.LBB0_1058:
	v_readlane_b32 s2, v248, 33
	v_readlane_b32 s3, v248, 34
	v_readlane_b32 s40, v250, 12
	s_andn2_b64 vcc, exec, s[2:3]
	v_readlane_b32 s44, v250, 16
	v_readlane_b32 s45, v250, 17
	v_readlane_b32 s46, v250, 18
	v_readlane_b32 s47, v250, 19
	v_readlane_b32 s41, v250, 13
	v_readlane_b32 s42, v250, 14
	v_readlane_b32 s43, v250, 15
	v_readlane_b32 s48, v250, 20
	v_readlane_b32 s49, v250, 21
	v_readlane_b32 s50, v250, 22
	v_readlane_b32 s51, v250, 23
	v_readlane_b32 s52, v250, 24
	v_readlane_b32 s53, v250, 25
	v_readlane_b32 s54, v250, 26
	v_readlane_b32 s55, v250, 27
	s_cbranch_vccnz .LBB0_1094
	v_mov_b32_e32 v4, v204
	v_readlane_b32 s3, v248, 35
	v_readfirstlane_b32 s2, v4
	s_ashr_i32 s2, s2, 6
	s_min_u32 s8, s81, 0x6ef6
	s_add_i32 s3, s3, s81
	s_addk_i32 s8, 0x410a
	s_add_i32 s9, s3, s2
	s_cmp_ge_i32 s9, s8
	s_cbranch_scc1 .LBB0_1094
	v_lshlrev_b32_e32 v0, 2, v4
	s_mulk_i32 s2, 0x4100
	v_bfe_u32 v1, v4, 4, 2
	v_and_b32_e32 v0, 60, v0
	s_add_i32 s2, s2, 0
	v_lshlrev_b32_e32 v3, 2, v0
	v_mul_u32_u24_e32 v5, 0x104, v1
	v_add3_u32 v3, s2, v3, v5
	v_and_b32_e32 v5, 7, v4
	v_bfe_u32 v13, v4, 3, 3
	v_lshlrev_b32_e32 v12, 3, v5
	v_mul_u32_u24_e32 v4, 0x820, v5
	v_lshlrev_b32_e32 v5, 2, v13
	v_add3_u32 v16, s2, v4, v5
	v_or_b32_e32 v17, 8, v13
	v_or_b32_e32 v18, 16, v13
	v_or_b32_e32 v19, 24, v13
	v_or_b32_e32 v20, 32, v13
	v_or_b32_e32 v21, 40, v13
	v_or_b32_e32 v22, 48, v13
	v_or_b32_e32 v23, 56, v13
	s_lshl_b32 s10, s9, 6
	s_lshl_b32 s11, s9, 1
	s_branch .LBB0_1064
